# index step A: hipcc's cascaded phi-copy lowering of the per-pair K[2jp],K[2jp+1] register store (up to 192 v_mov per iteration) replaced by a 4-level scalar branch tree with 8 v_mov per leaf
# speedup vs baseline: 1.0125x; 1.0125x over previous
.LBB0_1292:
	s_waitcnt vmcnt(0)
	v_cndmask_b32_e64 v19, 0, 1, s[78:79]
	v_cmp_ne_u32_e64 s[28:29], 1, v19
	s_andn2_b64 vcc, exec, s[78:79]
	v_lshlrev_b32_e32 v39, 4, v36
	v_lshlrev_b32_e32 v172, 2, v167
	v_lshl_add_u32 v40, v167, 13, 0
	v_lshl_add_u32 v41, v18, 2, s14
	s_waitcnt vmcnt(0) lgkmcnt(0)
	s_barrier
	s_cbranch_vccnz .LBB0_1383
	s_add_i32 s0, s77, 8
	s_lshr_b32 s1, s0, 29
	s_add_i32 s0, s0, s1
	s_ashr_i32 s13, s0, 3
	s_add_i32 s0, 0, 0x22200
	v_add_u32_e32 v173, s0, v39
	v_readlane_b32 s0, v251, 29
	s_add_i32 s14, s13, -2
	s_add_i32 s15, s13, -3
	v_add_u32_e32 v174, s0, v39
	s_max_i32 s0, s13, 2
	s_lshl_b32 s0, s0, 3
	s_add_i32 s0, s0, -8
	s_and_b32 s16, s0, -16
	v_or_b32_e32 v175, s24, v167
	s_add_i32 s16, s16, 16
	s_mov_b32 s17, 0
	v_mov_b64_e32 v[42:43], 0
	v_mov_b64_e32 v[44:45], 0
	v_mov_b64_e32 v[46:47], 0
	v_mov_b64_e32 v[48:49], 0
	v_mov_b64_e32 v[50:51], 0
	v_mov_b64_e32 v[52:53], 0
	v_mov_b64_e32 v[54:55], 0
	v_mov_b64_e32 v[56:57], 0
	v_mov_b64_e32 v[58:59], 0
	v_mov_b64_e32 v[60:61], 0
	v_mov_b64_e32 v[62:63], 0
	v_mov_b64_e32 v[64:65], 0
	v_mov_b64_e32 v[66:67], 0
	v_mov_b64_e32 v[68:69], 0
	v_mov_b64_e32 v[70:71], 0
	v_mov_b64_e32 v[72:73], 0
	v_mov_b64_e32 v[74:75], 0
	v_mov_b64_e32 v[76:77], 0
	v_mov_b64_e32 v[78:79], 0
	v_mov_b64_e32 v[80:81], 0
	v_mov_b64_e32 v[82:83], 0
	v_mov_b64_e32 v[84:85], 0
	v_mov_b64_e32 v[86:87], 0
	v_mov_b64_e32 v[88:89], 0
	v_mov_b64_e32 v[90:91], 0
	v_mov_b64_e32 v[92:93], 0
	v_mov_b64_e32 v[94:95], 0
	v_mov_b64_e32 v[96:97], 0
	v_mov_b64_e32 v[98:99], 0
	v_mov_b64_e32 v[100:101], 0
	v_mov_b64_e32 v[102:103], 0
	v_mov_b64_e32 v[104:105], 0
	v_mov_b64_e32 v[106:107], 0
	v_mov_b64_e32 v[108:109], 0
	v_mov_b64_e32 v[110:111], 0
	v_mov_b64_e32 v[112:113], 0
	v_mov_b64_e32 v[114:115], 0
	v_mov_b32_e32 v117, 0
	v_mov_b64_e32 v[118:119], 0
	v_mov_b64_e32 v[120:121], 0
	v_mov_b64_e32 v[122:123], 0
	v_mov_b64_e32 v[124:125], 0
	v_mov_b64_e32 v[126:127], 0
	v_mov_b64_e32 v[128:129], 0
	v_mov_b64_e32 v[130:131], 0
	v_mov_b64_e32 v[132:133], 0
	v_mov_b64_e32 v[134:135], 0
	v_mov_b64_e32 v[136:137], 0
	v_mov_b64_e32 v[138:139], 0
	v_mov_b64_e32 v[140:141], 0
	v_mov_b64_e32 v[142:143], 0
	v_mov_b64_e32 v[144:145], 0
	v_mov_b64_e32 v[146:147], 0
	v_mov_b64_e32 v[148:149], 0
	v_mov_b64_e32 v[150:151], 0
	v_mov_b64_e32 v[152:153], 0
	v_mov_b64_e32 v[154:155], 0
	v_mov_b64_e32 v[156:157], 0
	v_mov_b64_e32 v[158:159], 0
	v_mov_b64_e32 v[160:161], 0
	v_mov_b64_e32 v[162:163], 0
	v_mov_b64_e32 v[164:165], 0
	v_mov_b32_e32 v166, 0
	v_mov_b64_e32 v[168:169], 0
	v_mov_b64_e32 v[170:171], 0
	v_mov_b32_e32 v176, v41
	s_mov_b32 s18, 0
	s_mov_b32 s19, 0
	s_branch .LBB0_1296
.LBB0_1295:
	s_add_i32 s19, s19, 1
	s_add_i32 s18, s18, 2
	s_add_i32 s17, s17, 16
	s_cmp_eq_u32 s16, s17
	v_add_u32_e32 v176, 0x100, v176
	s_cbranch_scc1 .LBB0_1384

.LBB0_1320:
	s_or_b64 exec, exec, s[0:1]
	s_cmp_lt_i32 s19, 8
	s_cbranch_scc1 .Lksw_t0_8
	s_cmp_lt_i32 s19, 12
	s_cbranch_scc1 .Lksw_t8_12
	s_cmp_lt_i32 s19, 14
	s_cbranch_scc1 .Lksw_t12_14
	s_cmp_lt_i32 s19, 15
	s_cbranch_scc1 .Lksw_14
	s_cmp_eq_u32 s19, 15
	s_cbranch_scc0 .LBB0_1295
	v_mov_b32_e32 v42, v25
	v_mov_b32_e32 v43, v24
	v_mov_b32_e32 v44, v22
	v_mov_b32_e32 v45, v21
	v_mov_b32_e32 v46, v23
	v_mov_b32_e32 v47, v20
	v_mov_b32_e32 v48, v19
	v_mov_b32_e32 v49, v18
	s_branch .LBB0_1295
.Lksw_14:
	v_mov_b32_e32 v50, v25
	v_mov_b32_e32 v51, v24
	v_mov_b32_e32 v52, v22
	v_mov_b32_e32 v53, v21
	v_mov_b32_e32 v54, v23
	v_mov_b32_e32 v55, v20
	v_mov_b32_e32 v56, v19
	v_mov_b32_e32 v57, v18
	s_branch .LBB0_1295
.Lksw_t12_14:
	s_cmp_lt_i32 s19, 13
	s_cbranch_scc1 .Lksw_12
	v_mov_b32_e32 v58, v25
	v_mov_b32_e32 v59, v24
	v_mov_b32_e32 v60, v22
	v_mov_b32_e32 v61, v21
	v_mov_b32_e32 v62, v23
	v_mov_b32_e32 v63, v20
	v_mov_b32_e32 v64, v19
	v_mov_b32_e32 v65, v18
	s_branch .LBB0_1295
.Lksw_12:
	v_mov_b32_e32 v66, v25
	v_mov_b32_e32 v67, v24
	v_mov_b32_e32 v68, v22
	v_mov_b32_e32 v69, v21
	v_mov_b32_e32 v70, v23
	v_mov_b32_e32 v71, v20
	v_mov_b32_e32 v72, v19
	v_mov_b32_e32 v73, v18
	s_branch .LBB0_1295
.Lksw_t8_12:
	s_cmp_lt_i32 s19, 10
	s_cbranch_scc1 .Lksw_t8_10
	s_cmp_lt_i32 s19, 11
	s_cbranch_scc1 .Lksw_10
	v_mov_b32_e32 v74, v25
	v_mov_b32_e32 v75, v24
	v_mov_b32_e32 v76, v22
	v_mov_b32_e32 v77, v21
	v_mov_b32_e32 v78, v23
	v_mov_b32_e32 v79, v20
	v_mov_b32_e32 v80, v19
	v_mov_b32_e32 v81, v18
	s_branch .LBB0_1295
.Lksw_10:
	v_mov_b32_e32 v82, v25
	v_mov_b32_e32 v83, v24
	v_mov_b32_e32 v84, v22
	v_mov_b32_e32 v85, v21
	v_mov_b32_e32 v86, v23
	v_mov_b32_e32 v87, v20
	v_mov_b32_e32 v88, v19
	v_mov_b32_e32 v89, v18
	s_branch .LBB0_1295
.Lksw_t8_10:
	s_cmp_lt_i32 s19, 9
	s_cbranch_scc1 .Lksw_8
	v_mov_b32_e32 v90, v25
	v_mov_b32_e32 v91, v24
	v_mov_b32_e32 v92, v22
	v_mov_b32_e32 v93, v21
	v_mov_b32_e32 v94, v23
	v_mov_b32_e32 v95, v20
	v_mov_b32_e32 v96, v19
	v_mov_b32_e32 v97, v18
	s_branch .LBB0_1295
.Lksw_8:
	v_mov_b32_e32 v98, v25
	v_mov_b32_e32 v99, v24
	v_mov_b32_e32 v100, v22
	v_mov_b32_e32 v101, v21
	v_mov_b32_e32 v102, v23
	v_mov_b32_e32 v103, v20
	v_mov_b32_e32 v104, v19
	v_mov_b32_e32 v106, v18
	s_branch .LBB0_1295
.Lksw_t0_8:
	s_cmp_lt_i32 s19, 4
	s_cbranch_scc1 .Lksw_t0_4
	s_cmp_lt_i32 s19, 6
	s_cbranch_scc1 .Lksw_t4_6
	s_cmp_lt_i32 s19, 7
	s_cbranch_scc1 .Lksw_6
	v_mov_b32_e32 v105, v25
	v_mov_b32_e32 v107, v24
	v_mov_b32_e32 v108, v22
	v_mov_b32_e32 v109, v21
	v_mov_b32_e32 v110, v23
	v_mov_b32_e32 v111, v20
	v_mov_b32_e32 v112, v19
	v_mov_b32_e32 v113, v18
	s_branch .LBB0_1295
.Lksw_6:
	v_mov_b32_e32 v114, v25
	v_mov_b32_e32 v115, v24
	v_mov_b32_e32 v117, v22
	v_mov_b32_e32 v118, v21
	v_mov_b32_e32 v119, v23
	v_mov_b32_e32 v120, v20
	v_mov_b32_e32 v121, v19
	v_mov_b32_e32 v122, v18
	s_branch .LBB0_1295
.Lksw_t4_6:
	s_cmp_lt_i32 s19, 5
	s_cbranch_scc1 .Lksw_4
	v_mov_b32_e32 v123, v25
	v_mov_b32_e32 v124, v24
	v_mov_b32_e32 v125, v22
	v_mov_b32_e32 v126, v21
	v_mov_b32_e32 v127, v23
	v_mov_b32_e32 v128, v20
	v_mov_b32_e32 v129, v19
	v_mov_b32_e32 v130, v18
	s_branch .LBB0_1295
.Lksw_4:
	v_mov_b32_e32 v131, v25
	v_mov_b32_e32 v132, v24
	v_mov_b32_e32 v133, v22
	v_mov_b32_e32 v134, v21
	v_mov_b32_e32 v135, v23
	v_mov_b32_e32 v136, v20
	v_mov_b32_e32 v137, v19
	v_mov_b32_e32 v138, v18
	s_branch .LBB0_1295
.Lksw_t0_4:
	s_cmp_lt_i32 s19, 2
	s_cbranch_scc1 .Lksw_t0_2
	s_cmp_lt_i32 s19, 3
	s_cbranch_scc1 .Lksw_2
	v_mov_b32_e32 v139, v25
	v_mov_b32_e32 v140, v24
	v_mov_b32_e32 v141, v22
	v_mov_b32_e32 v142, v21
	v_mov_b32_e32 v143, v23
	v_mov_b32_e32 v144, v20
	v_mov_b32_e32 v145, v19
	v_mov_b32_e32 v146, v18
	s_branch .LBB0_1295
.Lksw_2:
	v_mov_b32_e32 v147, v25
	v_mov_b32_e32 v148, v24
	v_mov_b32_e32 v149, v22
	v_mov_b32_e32 v150, v21
	v_mov_b32_e32 v151, v23
	v_mov_b32_e32 v152, v20
	v_mov_b32_e32 v153, v19
	v_mov_b32_e32 v154, v18
	s_branch .LBB0_1295
.Lksw_t0_2:
	s_cmp_lt_i32 s19, 1
	s_cbranch_scc1 .Lksw_0
	v_mov_b32_e32 v155, v25
	v_mov_b32_e32 v156, v24
	v_mov_b32_e32 v157, v22
	v_mov_b32_e32 v158, v21
	v_mov_b32_e32 v159, v23
	v_mov_b32_e32 v160, v20
	v_mov_b32_e32 v161, v19
	v_mov_b32_e32 v162, v18
	s_branch .LBB0_1295
.Lksw_0:
	v_mov_b32_e32 v163, v25
	v_mov_b32_e32 v164, v24
	v_mov_b32_e32 v165, v22
	v_mov_b32_e32 v166, v21
	v_mov_b32_e32 v168, v23
	v_mov_b32_e32 v169, v20
	v_mov_b32_e32 v170, v19
	v_mov_b32_e32 v171, v18
	s_branch .LBB0_1295
